# MLA fast path: removed the remaining per-segment s_setprio flips
# speedup vs baseline: 1.0445x; 1.0023x over previous
; template <bool DIFF>
; DI void attn_phase(const AttnArgs& a, char* lds) {
;     ...
;     for (int t = t_beg; t < t_end; ++t) {
;       const char* sb = lds + (t & 1) * STAGE;
;       char* nb = lds + ((t + 1) & 1) * STAGE;
;       const bool nxt = t + 1 < t_end;
;       const int4 tinfo = *(const int4*)(ttab + 4 * t);
;       const int kcmin = __builtin_amdgcn_readfirstlane(tinfo.x), kcmax = __builtin_amdgcn_readfirstlane(tinfo.y);
;       bool skip = kcmin > wqcmax;
;       if (DIFF) {
;         const int tpmin = __builtin_amdgcn_readfirstlane(tinfo.z), tpmax = __builtin_amdgcn_readfirstlane(tinfo.w);
;         const int dist = max(0, max(wpmin - tpmax, tpmin - wpmax));
;         skip = skip || (slope2 * (float)dist > lim2);
;       }
;       const bool needmask = kcmax > wqcmin;
;       if (nxt) {
;         const int t2 = tid_pinned();
;         const u32 kofs = KOFS(t2), vofs = VOFS(t2);
;         const u32 ko2 = kofs + (u32)(t + 1) * 64u * (u32)a.ldk;
; #pragma unroll
;         for (int i = 0; i < NKR; ++i) GLDS16(a.K + ko2 + i * 64, nb + wave * 1024 + 8192 * i);
;         const u32 vo2 = vofs + (u32)(t + 1) * (u32)(DV * 64);
; #pragma unroll
;         for (int i = 0; i < NVR; ++i) GLDS16(a.VT + vo2 + i * 4096, nb + KBYTES + wave * 1024 + 8192 * i);
;         if (wave == 0) { const int l4 = (t + 1) * 64 + (t2 & 63); GLDS4(a.pos + l4, nb + KBYTES + VBYTES); GLDS4(a.posf + l4, nb + KBYTES + VBYTES + 256); }
;       }
;       int uft = usefix_i; asm volatile("" : "+v"(uft)); uft = __builtin_amdgcn_readfirstlane(uft);
;       if (!DIFF && uft != 0 && !skip) {
;         const int* pki = (const int*)(sb + KBYTES + VBYTES);
;         const int l2 = tid_pinned() & 63, l31b = l2 & 31, g2 = l2 >> 5;
;         const int prow = (((l31b >> 4) & 1) << 4) | (((l31b >> 2) & 1) << 3) | (((l31b >> 3) & 1) << 2) | (l31b & 3);
;         const int kx = g2 ^ ((prow >> 1) & 7);
;         const int koffb = prow * 128;
;         const int vx = g2 ^ ((l31b >> 1) & 7);
;         const int voffb = KBYTES + l31b * 128;
;         bf16x8 kf[NDS];
; #pragma unroll
;         for (int ds = 0; ds < NDS; ++ds) kf[ds] = *(const bf16x8*)(sb + koffb + (ds >> 2) * 8192 + ((((ds & 3) * 2) ^ kx) << 4));
;         f32x16 s0, s1;
;         __builtin_amdgcn_s_setprio(1);
;         s0 = MFMA(kf[0], qf[0], negm);
; #pragma unroll
;         for (int ds = 1; ds < NDS; ++ds) s0 = MFMA(kf[ds], qf[ds], s0);
.LBB0_376:
	s_add_i32 s10, s7, -4
	v_mov_b32_e32 v0, s10
	ds_read_b64 v[2:3], v0
	s_add_i32 s53, s22, 1
	s_bitcmp1_b32 s53, 0
	s_cselect_b32 s85, 0xa200, 0
	s_add_i32 s88, s85, s59
	s_waitcnt lgkmcnt(0)
	v_readfirstlane_b32 s11, v2
	v_readfirstlane_b32 s10, v3
	s_bitcmp1_b32 s22, 0
	v_mov_b32_e32 v0, v214
	s_cselect_b32 s63, 0xa200, 0
	s_cmp_gt_i32 s11, s1
	s_nop 0
	s_cselect_b64 s[74:75], -1, 0
	v_readfirstlane_b32 s22, v0
	s_cmp_eq_u32 s22, 0
	s_cselect_b64 s[86:87], -1, 0
	v_cmp_gt_i32_e64 s[10:11], s10, v213
	s_or_b64 s[86:87], s[86:87], s[74:75]
	s_and_b64 vcc, exec, s[86:87]
	v_cndmask_b32_e64 v0, 0, 1, s[10:11]
	v_cmp_ne_u32_e64 s[10:11], 1, v0
	s_cbranch_vccnz .Lmla_slow
	v_mov_b32_e32 v0, v208
	s_nop 0
	v_lshlrev_b32_e32 v2, 1, v0
	v_lshrrev_b32_e32 v3, 1, v0
	v_and_b32_e32 v2, 8, v2
	v_and_b32_e32 v3, 4, v3
	v_and_b32_e32 v4, 19, v0
	v_or3_b32 v2, v2, v4, v3
	v_bfe_u32 v15, v0, 5, 1
	v_lshrrev_b32_e32 v3, 1, v2
	v_bitop3_b32 v3, v3, v15, 7 bitop3:0x6c
	v_lshl_add_u32 v2, v2, 7, s63
	v_lshlrev_b32_e32 v3, 4, v3
	v_add_u32_e32 v172, v2, v3
	v_xad_u32 v176, v3, 32, v2
	v_xad_u32 v180, v3, 64, v2
	v_xad_u32 v226, v3, s82, v2
	ds_read_b128 v[2:5], v172
	ds_read_b128 v[84:87], v176
	ds_read_b128 v[10:13], v180
	ds_read_b128 v[164:167], v226
	ds_read_b128 v[6:9], v172 offset:8192
	ds_read_b128 v[92:95], v176 offset:8192
	ds_read_b128 v[80:83], v180 offset:8192
	ds_read_b128 v[168:171], v226 offset:8192
	ds_read_b128 v[88:91], v172 offset:16384
	ds_read_b128 v[160:163], v176 offset:16384
	ds_read_b128 v[218:221], v180 offset:16384
	ds_read_b128 v[222:225], v226 offset:16384
	v_lshrrev_b32_e32 v14, 5, v0
	v_bfe_u32 v96, v0, 1, 3
	v_lshlrev_b32_e32 v0, 7, v0
	v_and_b32_e32 v0, 0xf80, v0
	v_bitop3_b32 v14, v14, v96, 1 bitop3:0x6c
	v_lshrrev_b32_e32 v228, 4, v208
	v_xor_b32_e32 v228, v228, v208
	v_ashrrev_i32_e32 v230, 3, v208
	v_lshlrev_b32_e32 v228, 3, v228
	v_and_b32_e32 v231, 56, v228
	v_add_u32_e32 v228, s52, v230
	v_mul_lo_u32 v228, v228, s76
	v_mov_b32_e32 v229, 0
	v_add_u32_e32 v228, s4, v228
	v_or_b32_e32 v228, v228, v231
	v_lshl_add_u64 v[232:233], v[228:229], 1, s[14:15]
	v_lshl_or_b32 v228, v230, 6, v231
	v_add_u32_e32 v228, s5, v228
	v_lshl_add_u64 v[234:235], v[232:233], 0, s[16:17]
	v_lshl_add_u64 v[236:237], v[232:233], 0, s[18:19]
	v_lshl_add_u64 v[238:239], v[228:229], 1, s[40:41]
	v_lshl_add_u64 v[240:241], v[238:239], 0, s[68:69]
	v_and_b32_e32 v242, 63, v208
	v_add_u32_e32 v242, s52, v242
	v_ashrrev_i32_e32 v243, 31, v242
	v_lshlrev_b64 v[242:243], 2, v[242:243]
	v_lshl_add_u64 v[244:245], s[48:49], 0, v[242:243]
	v_lshl_add_u64 v[242:243], s[38:39], 0, v[242:243]
	s_add_i32 s89, s88, 0x2000
	s_add_i32 s90, s88, 0x4000
	s_add_i32 s91, s88, 0x6000
	s_add_i32 s32, s88, 0x8000
	s_cmp_ge_i32 s53, s0
	s_cselect_b64 vcc, -1, 0
	s_mov_b32 m0, s88
	s_waitcnt lgkmcnt(11)
	v_mfma_f32_32x32x16_bf16 v[96:111], v[2:5], v[112:115], 0
	s_cbranch_vccnz .Lmla_nd1
	global_load_lds_dwordx4 v[232:233], off

; #define MFMA(a, b, c) __builtin_amdgcn_mfma_f32_32x32x16_bf16((a), (b), (c), 0, 0, 0)
; DI u32 pk2(float a, float b) { f2_t v = {a, b}; bf2_t r = __builtin_convertvector(v, bf2_t); return __builtin_bit_cast(u32, r); }
; template <bool DIFF>
; DI void attn_phase(const AttnArgs& a, char* lds) {
;     ...
;         {
; #pragma unroll
;           for (int m = 0; m < NM; ++m) vf[1][m] = *(const bf16x8*)(sb + voffb + m * 4096 + ((2 ^ vx) << 4));
; #pragma unroll
;           for (int s2 = 0; s2 < 2; ++s2) {
;             u32x4 pw;
;             pw[0] = pk2(s0[8 * s2], s0[8 * s2 + 1]); pw[1] = pk2(s0[8 * s2 + 2], s0[8 * s2 + 3]);
;             pw[2] = pk2(s0[8 * s2 + 4], s0[8 * s2 + 5]); pw[3] = pk2(s0[8 * s2 + 6], s0[8 * s2 + 7]);
;             const bf16x8 pf = __builtin_bit_cast(bf16x8, pw);
;             __builtin_amdgcn_s_setprio(1);
; #pragma unroll
;             for (int m = 0; m < NM; ++m) o[m] = MFMA(vf[s2][m], pf, o[m]);
;             __builtin_amdgcn_s_setprio(0);
;           }
;           float ps = 0.f;
; #pragma unroll
;           for (int r = 0; r < 16; ++r) { s1[r] = __builtin_amdgcn_exp2f(s1[r]); ps += s1[r]; }
;           l_sum += ps;
;           asm volatile("" : "+v"(l_sum));
; #pragma unroll
;           for (int s2 = 0; s2 < 2; ++s2)
; #pragma unroll
;             for (int m = 0; m < NM; ++m) vf[s2][m] = *(const bf16x8*)(sb + voffb + m * 4096 + (((4 + 2 * s2) ^ vx) << 4));
;           __builtin_amdgcn_sched_group_barrier(0x002, 8, 0);
; #pragma unroll
;           for (int i = 0; i < 2 * NM; ++i) { __builtin_amdgcn_sched_group_barrier(0x008, 1, 0); __builtin_amdgcn_sched_group_barrier(0x002, 5, 0); }
;         }
;         __builtin_amdgcn_sched_barrier(0);
;         {
; #pragma unroll
;           for (int s2 = 0; s2 < 2; ++s2) {
;             u32x4 pw;
;             pw[0] = pk2(s1[8 * s2], s1[8 * s2 + 1]); pw[1] = pk2(s1[8 * s2 + 2], s1[8 * s2 + 3]);
;             pw[2] = pk2(s1[8 * s2 + 4], s1[8 * s2 + 5]); pw[3] = pk2(s1[8 * s2 + 6], s1[8 * s2 + 7]);
;             const bf16x8 pf = __builtin_bit_cast(bf16x8, pw);
;             __builtin_amdgcn_s_setprio(1);
; #pragma unroll
;             for (int m = 0; m < NM; ++m) o[m] = MFMA(vf[s2][m], pf, o[m]);
;             __builtin_amdgcn_s_setprio(0);
;           }
;         }
.LBB0_384:
	v_xad_u32 v15, v14, 32, v0
	ds_read_b128 v[164:167], v15 offset:24576
	ds_read_b128 v[168:171], v15 offset:28672
	ds_read_b128 v[172:175], v15 offset:32768
	ds_read_b128 v[176:179], v15 offset:36864
	v_cvt_pk_bf16_f32 v180, v218, v97
	v_cvt_pk_bf16_f32 v181, v98, v99
	v_cvt_pk_bf16_f32 v182, v100, v101
	v_cvt_pk_bf16_f32 v183, v102, v204
	v_cvt_pk_bf16_f32 v248, v103, v104
	v_cvt_pk_bf16_f32 v249, v105, v106
	v_cvt_pk_bf16_f32 v250, v107, v108
	v_cvt_pk_bf16_f32 v251, v109, v110
	v_xad_u32 v227, v14, 64, v0
	v_xad_u32 v0, v14, s82, v0
	v_mfma_f32_32x32x16_bf16 v[64:79], v[160:163], v[180:183], v[64:79]
	v_exp_f32_e32 v15, v80
	v_exp_f32_e32 v100, v81
	v_add_f32_e32 v252, 0, v15
	v_add_f32_e32 v252, v100, v252
	v_mfma_f32_32x32x16_bf16 v[48:63], v[10:13], v[180:183], v[48:63]
	v_exp_f32_e32 v101, v82
	v_exp_f32_e32 v102, v83
	v_add_f32_e32 v252, v101, v252
	v_add_f32_e32 v252, v102, v252
	v_mfma_f32_32x32x16_bf16 v[32:47], v[6:9], v[180:183], v[32:47]
	v_exp_f32_e32 v103, v84
	v_exp_f32_e32 v104, v85
	v_add_f32_e32 v252, v103, v252
	v_add_f32_e32 v252, v104, v252
	v_mfma_f32_32x32x16_bf16 v[16:31], v[2:5], v[180:183], v[16:31]
	ds_read_b128 v[2:5], v227 offset:24576
	ds_read_b128 v[6:9], v227 offset:28672
	ds_read_b128 v[10:13], v227 offset:32768
	ds_read_b128 v[228:231], v227 offset:36864
	v_exp_f32_e32 v105, v86
	v_exp_f32_e32 v106, v87
	v_add_f32_e32 v252, v105, v252
	v_add_f32_e32 v252, v106, v252
	s_waitcnt lgkmcnt(4)
	v_mfma_f32_32x32x16_bf16 v[64:79], v[164:167], v[248:251], v[64:79]
	ds_read_b128 v[232:235], v0 offset:24576
	ds_read_b128 v[236:239], v0 offset:28672
	ds_read_b128 v[240:243], v0 offset:32768
	ds_read_b128 v[244:247], v0 offset:36864
	v_exp_f32_e32 v107, v88
	v_exp_f32_e32 v108, v89
	v_add_f32_e32 v252, v107, v252
	v_add_f32_e32 v252, v108, v252
	v_mfma_f32_32x32x16_bf16 v[48:63], v[168:171], v[248:251], v[48:63]
	v_exp_f32_e32 v109, v90
	v_exp_f32_e32 v110, v91
	v_add_f32_e32 v252, v109, v252
	v_add_f32_e32 v252, v110, v252
	v_mfma_f32_32x32x16_bf16 v[32:47], v[172:175], v[248:251], v[32:47]
	v_exp_f32_e32 v111, v92
	v_exp_f32_e32 v160, v93
	v_add_f32_e32 v252, v111, v252
	v_add_f32_e32 v252, v160, v252
	v_mfma_f32_32x32x16_bf16 v[16:31], v[176:179], v[248:251], v[16:31]
	v_exp_f32_e32 v161, v94
	v_exp_f32_e32 v162, v95
	v_add_f32_e32 v252, v161, v252
	v_add_f32_e32 v252, v162, v252
	v_add_f32_e32 v217, v96, v252
	v_cvt_pk_bf16_f32 v100, v15, v100
	v_cvt_pk_bf16_f32 v101, v101, v102
	v_cvt_pk_bf16_f32 v102, v103, v104
	v_cvt_pk_bf16_f32 v103, v105, v106
	v_cvt_pk_bf16_f32 v248, v107, v108
	v_cvt_pk_bf16_f32 v249, v109, v110
	v_cvt_pk_bf16_f32 v250, v111, v160
	v_cvt_pk_bf16_f32 v251, v161, v162
	s_waitcnt lgkmcnt(0)
	v_mfma_f32_32x32x16_bf16 v[64:79], v[2:5], v[100:103], v[64:79]
	v_mfma_f32_32x32x16_bf16 v[48:63], v[6:9], v[100:103], v[48:63]
	v_mfma_f32_32x32x16_bf16 v[32:47], v[10:13], v[100:103], v[32:47]
	v_mfma_f32_32x32x16_bf16 v[16:31], v[228:231], v[100:103], v[16:31]
	v_mfma_f32_32x32x16_bf16 v[64:79], v[232:235], v[248:251], v[64:79]
	v_mfma_f32_32x32x16_bf16 v[48:63], v[236:239], v[248:251], v[48:63]
	v_mfma_f32_32x32x16_bf16 v[32:47], v[240:243], v[248:251], v[32:47]
	v_mfma_f32_32x32x16_bf16 v[16:31], v[244:247], v[248:251], v[16:31]
